# P5 tail split-K on both layers (64 CUs, slab exchange), PP skip 64
# baseline (speedup 1.0000x reference)
;     __device__ __forceinline__ bool next(int i, Unit& u) const {
;         if (v < nskip) return false;
;         const int L = i * (G - nskip) + (v - nskip); if (L >= (33792 / BM) * NN) return false;
;         constexpr int NM = 33792 / BM, NFULL = (NM / 8) * 8 * NN;
;         if (L < NFULL) { const int g = L / (8 * NN), idx = L % (8 * NN); u.pm = g * 8 + (idx & 7); u.pn = idx >> 3; }
; template <int l>
; __device__ __forceinline__ void run_layer(LAS unsigned char* lds, unsigned char* ws_in, float* out_in, const float* x_p, const float* x_s, const PIn* pin, const int G, const int bid, const int wave) {
;     ...
;             pg8::RowOrderSkip<DM / 256> S2; S2.init(G, bid, (G > 16) ? (MT / 256 * 4) % G : 0);
;             EpiPP E2{ws, out};
;             pg8::gemm_phase<DPLE, EpiPP, pg8::RowOrderSkip<DM / 256>>(lds, (const bf16*)(ws + WS_PB) + (size_t)l * MT * DPLE, (const bf16*)(wb + W_PP), S2, E2, wave);
.LBB0_646:
	s_cmp_gt_i32 s64, 16
	s_cselect_b64 s[2:3], -1, 0
	v_writelane_b32 v249, s2, 52
	v_mov_b32_e32 v0, v196
	s_nop 0
	v_writelane_b32 v249, s3, 53
	s_and_b64 s[2:3], s[2:3], exec
	s_cselect_b32 s14, s8, 0
	s_cmp_eq_u32 s64, 0x100
	s_cselect_b32 s14, 64, s14
	s_cmp_lt_i32 s1, s14
	s_cbranch_scc1 .LBB0_700
	s_sub_i32 s1, s1, s14
	s_cmpk_gt_i32 s1, 0x20f
	s_cbranch_scc1 .LBB0_700
	s_cmpk_gt_i32 s1, 0x1ff
	s_cbranch_scc0 .LBB0_680
	s_add_i32 s2, s1, 0xfffffe00
	s_and_b32 s3, s1, 3
	s_or_b32 s56, s3, 0x80
	s_lshr_b32 s54, s2, 2
	s_cbranch_execz .LBB0_681
	s_branch .LBB0_682

;     __device__ __forceinline__ bool next(int i, Unit& u) const {
;         constexpr int NU = (33792 / BM) * NN;
;         const int L = i * G + ((NU - i * G < G) ? vp : v); if (L >= NU) return false;
;         constexpr int NM = 33792 / BM, NFULL = (NM / 8) * 8 * NN;
;         if (L < NFULL) { const int g = L / (8 * NN), idx = L % (8 * NN); u.pm = g * 8 + (idx & 7); u.pn = idx >> 3; }
;         else { constexpr int GS = NM % 8 ? NM % 8 : 8; const int idx = L - NFULL; u.pm = (NM / 8) * 8 + idx % GS; u.pn = idx / GS; }
;         return true;
;     }
; template <int KK, class Epi, class Sched, bool ALIGN_EPI = true>
; __device__ __forceinline__ void gemm_phase(LAS unsigned char* lds, const bf16* gA, const bf16* gBt, const Sched& S, const Epi& E, const int wid) {
;     ...
;         const bool has_next = S.next(ui + 1, nxt);
;         const char* nA = has_next ? (const char*)gA + (size_t)nxt.pm * tstep : cA; const char* nB = has_next ? (const char*)gBt + (size_t)nxt.pn * tstep : cB;
.LBB0_661:
	s_add_i32 s41, s41, 1
	s_mul_i32 s6, s41, s64
	s_sub_i32 s7, 0x210, s6
	s_cmp_lt_i32 s7, s64
	s_cselect_b32 s18, s0, s1
	s_add_i32 s18, s18, s6
	s_cmp_lg_u32 s64, 0x100
	s_cbranch_scc1 .Lp5a_sch
	s_cmp_lg_u32 s41, 2
	s_cbranch_scc1 .Lp5a_sch
	s_movk_i32 s18, 0x210
	s_cmp_gt_u32 s86, 63
	s_cbranch_scc1 .Lp5a_sch
	s_and_b32 s7, s86, 7
	s_lshl_b32 s7, s7, 1
	s_bfe_u32 s18, s86, 0x10005
	s_add_i32 s18, s18, s7
	s_addk_i32 s18, 0x200
.Lp5a_sch:
	s_cmpk_lt_i32 s18, 0x210
	s_cselect_b64 s[16:17], -1, 0
	s_cmpk_gt_i32 s18, 0x20f
	s_cbranch_scc1 .LBB0_666
	s_cmpk_gt_i32 s18, 0x1ff
	s_mov_b64 s[6:7], -1
	s_cbranch_scc0 .LBB0_664
	s_add_i32 s6, s18, 0xfffffe00
	s_and_b32 s7, s18, 3
	s_or_b32 s63, s7, 0x80
	s_lshr_b32 s66, s6, 2
	s_mov_b64 s[6:7], 0

; #define PG8_STAGE(bufoff, gbase, voff) do { _Pragma("unroll") for (int _i = 0; _i < 2; ++_i) \
;         __builtin_amdgcn_global_load_lds((const unsigned*)((const char*)(gbase) + (voff)[_i]), (LAS unsigned*)(lds + (bufoff) + ldsw + _i * 8192), 16, 0, 0); } while (0)
; #define PG8_LDA(dst, b, h) do { _Pragma("unroll") for (int m = 0; m < 4; ++m) _Pragma("unroll") for (int k = 0; k < 2; ++k) dst[m][k] = *(const LAS bf16x8*)(lds + PG8_SA(b, h) + aoff + m * 2048 + k * 1024); } while (0)
; #define PG8_LDB(dst, b, h) do { _Pragma("unroll") for (int n = 0; n < 2; ++n) _Pragma("unroll") for (int k = 0; k < 2; ++k) dst[n][k] = *(const LAS bf16x8*)(lds + PG8_SB(b, h) + boff + n * 2048 + k * 1024); } while (0)
; #define PG8_WAIT_V(n) asm volatile("s_waitcnt vmcnt(" #n ")" ::: "memory")
; #define PG8_WAIT_L(n) asm volatile("s_waitcnt lgkmcnt(" #n ")" ::: "memory")
; #define PG8_BAR __builtin_amdgcn_s_barrier()
; #define PG8_SCHED __builtin_amdgcn_sched_barrier(0)
; template <int KK, class Epi, class Sched, bool ALIGN_EPI = true>
; __device__ __forceinline__ void gemm_phase(LAS unsigned char* lds, const bf16* gA, const bf16* gBt, const Sched& S, const Epi& E, const int wid) {
;     ...
;         const char* nA = has_next ? (const char*)gA + (size_t)nxt.pm * tstep : cA; const char* nB = has_next ? (const char*)gBt + (size_t)nxt.pn * tstep : cB;
; #pragma unroll 1
;         for (int t = 0; t < nt; t += 2) {
;             const bool last = (t == nt - 2);
;             const char* a1 = cA + (size_t)(t + 1) * kstep;
;             const char* a2 = last ? nA : cA + (size_t)(t + 2) * kstep; const char* b2 = last ? nB : cB + (size_t)(t + 2) * kstep;
;             const char* a3 = a2 + kstep; const char* b3 = b2 + kstep;
;             PG8_LDB(B0, 0, 0); PG8_LDB(B1, 0, 1); PG8_SCHED; PG8_LDA(At, 0, 0); PG8_STAGE(PG8_SA(1, 1), a1 + hstep, voffA);
;             PG8_WAIT_V(8); PG8_WAIT_L(0); PG8_BAR; PG8_MMA(0, 0, At, B0); PG8_MMA(0, 1, At, B1); PG8_BAR; PG8_SCHED;
;     ...
; #pragma unroll
;         for (int a = 0; a < 2; ++a)
; #pragma unroll
;             for (int b = 0; b < 2; ++b)
; #pragma unroll
;                 for (int m = 0; m < 4; ++m)
; #pragma unroll
;                     for (int n = 0; n < 2; ++n) acc[a][b][m][n] = (f32x4){0.f, 0.f, 0.f, 0.f};
;         cur = nxt; cA = nA; cB = nB; ++ui;
.LBB0_670:
	s_cmp_lg_u32 s64, 0x100
	s_cbranch_scc1 .Lp5a_kof
	s_cmp_lg_u32 s41, 2
	s_cbranch_scc1 .Lp5a_kof
	s_cmp_gt_u32 s86, 63
	s_cbranch_scc1 .Lp5a_kof
	s_bfe_u32 s82, s86, 0x20003
	s_mul_i32 s83, s82, 0x600
	s_cmp_eq_u32 s82, 3
	s_cselect_b32 s82, 0x100, 0
	s_sub_i32 s83, s83, s82
	s_add_u32 s16, s16, s83
	s_addc_u32 s17, s17, 0
	s_add_u32 s18, s18, s83
	s_addc_u32 s19, s19, 0
.Lp5a_kof:
	s_add_u32 s69, s42, 0x100
	v_mov_b32_e32 v0, 0
	s_addc_u32 s70, s43, 0
	s_mov_b32 s71, -2
	s_cmp_lg_u32 s64, 0x100
	s_cbranch_scc1 .Lp5a_cnt
	s_cmp_lg_u32 s41, 3
	s_cbranch_scc1 .Lp5a_cnt
	s_bfe_u32 s82, s86, 0x10004
	s_lshl_b32 s82, s82, 1
	s_add_i32 s71, s82, 30
.Lp5a_cnt:
	v_mov_b32_e32 v1, v0
	v_mov_b32_e32 v2, v0
	v_mov_b32_e32 v3, v0
	v_mov_b32_e32 v4, v0
	v_mov_b32_e32 v5, v0
	v_mov_b32_e32 v6, v0
	v_mov_b32_e32 v7, v0
	v_mov_b32_e32 v12, v0
	v_mov_b32_e32 v13, v0
	v_mov_b32_e32 v14, v0
	v_mov_b32_e32 v15, v0
	v_mov_b32_e32 v20, v0
	v_mov_b32_e32 v21, v0
	v_mov_b32_e32 v22, v0
	v_mov_b32_e32 v23, v0
	v_mov_b32_e32 v28, v0
	v_mov_b32_e32 v29, v0
	v_mov_b32_e32 v30, v0
	v_mov_b32_e32 v31, v0
	v_mov_b32_e32 v36, v0
	v_mov_b32_e32 v37, v0
	v_mov_b32_e32 v38, v0
	v_mov_b32_e32 v39, v0
	v_mov_b32_e32 v44, v0
	v_mov_b32_e32 v45, v0
	v_mov_b32_e32 v46, v0
	v_mov_b32_e32 v47, v0
	v_mov_b32_e32 v52, v0
	v_mov_b32_e32 v53, v0
	v_mov_b32_e32 v54, v0
	v_mov_b32_e32 v55, v0
	v_mov_b32_e32 v8, v0
	v_mov_b32_e32 v9, v0
	v_mov_b32_e32 v10, v0
	v_mov_b32_e32 v11, v0
	v_mov_b32_e32 v16, v0
	v_mov_b32_e32 v17, v0
	v_mov_b32_e32 v18, v0
	v_mov_b32_e32 v19, v0
	v_mov_b32_e32 v24, v0
	v_mov_b32_e32 v25, v0
	v_mov_b32_e32 v26, v0
	v_mov_b32_e32 v27, v0
	v_mov_b32_e32 v32, v0
	v_mov_b32_e32 v33, v0
	v_mov_b32_e32 v34, v0
	v_mov_b32_e32 v35, v0
	v_mov_b32_e32 v40, v0
	v_mov_b32_e32 v41, v0
	v_mov_b32_e32 v42, v0
	v_mov_b32_e32 v43, v0
	v_mov_b32_e32 v48, v0
	v_mov_b32_e32 v49, v0
	v_mov_b32_e32 v50, v0
	v_mov_b32_e32 v51, v0
	v_mov_b32_e32 v56, v0
	v_mov_b32_e32 v57, v0
	v_mov_b32_e32 v58, v0
	v_mov_b32_e32 v59, v0
	v_mov_b32_e32 v60, v0
	v_mov_b32_e32 v61, v0
	v_mov_b32_e32 v62, v0
	v_mov_b32_e32 v63, v0
	v_mov_b32_e32 v64, v0
	v_mov_b32_e32 v65, v0
	v_mov_b32_e32 v66, v0
	v_mov_b32_e32 v67, v0
	v_mov_b32_e32 v68, v0
	v_mov_b32_e32 v69, v0
	v_mov_b32_e32 v70, v0
	v_mov_b32_e32 v71, v0
	v_mov_b32_e32 v76, v0
	v_mov_b32_e32 v77, v0
	v_mov_b32_e32 v78, v0
	v_mov_b32_e32 v79, v0
	v_mov_b32_e32 v84, v0
	v_mov_b32_e32 v85, v0
	v_mov_b32_e32 v86, v0
	v_mov_b32_e32 v87, v0
	v_mov_b32_e32 v92, v0
	v_mov_b32_e32 v93, v0
	v_mov_b32_e32 v94, v0
	v_mov_b32_e32 v95, v0
	v_mov_b32_e32 v100, v0
	v_mov_b32_e32 v101, v0
	v_mov_b32_e32 v102, v0
	v_mov_b32_e32 v103, v0
	v_mov_b32_e32 v108, v0
	v_mov_b32_e32 v109, v0
	v_mov_b32_e32 v110, v0
	v_mov_b32_e32 v111, v0
	v_mov_b32_e32 v116, v0
	v_mov_b32_e32 v117, v0
	v_mov_b32_e32 v118, v0
	v_mov_b32_e32 v119, v0
	v_mov_b32_e32 v72, v0
	v_mov_b32_e32 v73, v0
	v_mov_b32_e32 v74, v0
	v_mov_b32_e32 v75, v0
	v_mov_b32_e32 v80, v0
	v_mov_b32_e32 v81, v0
	v_mov_b32_e32 v82, v0
	v_mov_b32_e32 v83, v0
	v_mov_b32_e32 v88, v0
	v_mov_b32_e32 v89, v0
	v_mov_b32_e32 v90, v0
	v_mov_b32_e32 v91, v0
	v_mov_b32_e32 v96, v0
	v_mov_b32_e32 v97, v0
	v_mov_b32_e32 v98, v0
	v_mov_b32_e32 v99, v0
	v_mov_b32_e32 v104, v0
	v_mov_b32_e32 v105, v0
	v_mov_b32_e32 v106, v0
	v_mov_b32_e32 v107, v0
	v_mov_b32_e32 v112, v0
	v_mov_b32_e32 v113, v0
	v_mov_b32_e32 v114, v0
	v_mov_b32_e32 v115, v0
	v_mov_b32_e32 v120, v0
	v_mov_b32_e32 v121, v0
	v_mov_b32_e32 v122, v0
	v_mov_b32_e32 v123, v0
	v_mov_b32_e32 v124, v0
	v_mov_b32_e32 v125, v0
	v_mov_b32_e32 v126, v0
	v_mov_b32_e32 v127, v0
.LBB0_671:
	ds_read_b128 v[140:143], v152
	ds_read_b128 v[144:147], v152 offset:1024
	ds_read_b128 v[148:151], v152 offset:2048
	ds_read_b128 v[158:161], v152 offset:3072
	ds_read_b128 v[162:165], v153
	ds_read_b128 v[166:169], v153 offset:1024
	ds_read_b128 v[170:173], v153 offset:2048
	ds_read_b128 v[174:177], v153 offset:3072
	s_add_u32 s42, s30, 0x100
	s_addc_u32 s43, s31, 0
	s_cmp_eq_u32 s71, 40
	s_cselect_b32 s55, s17, s43
	s_cselect_b32 s54, s16, s42
	s_cselect_b32 s53, s19, s70
	s_cselect_b32 s52, s18, s69
	s_mov_b32 m0, s49
	v_lshl_add_u64 v[194:195], s[30:31], 0, v[138:139]
	ds_read_b128 v[178:181], v154
	ds_read_b128 v[182:185], v154 offset:1024
	ds_read_b128 v[186:189], v154 offset:2048
	ds_read_b128 v[190:193], v154 offset:3072
	ds_read_b128 v[200:203], v154 offset:4096
	ds_read_b128 v[204:207], v154 offset:5120
	ds_read_b128 v[208:211], v154 offset:6144
	ds_read_b128 v[212:215], v154 offset:7168
	global_load_lds_dwordx4 v[194:195], off
	v_lshl_add_u64 v[194:195], s[30:31], 0, v[136:137]
	s_mov_b32 m0, s50
	s_nop 0
	global_load_lds_dwordx4 v[194:195], off
	s_waitcnt vmcnt(8)
	s_waitcnt lgkmcnt(0)
	s_barrier
; #define PG8_STAGE(bufoff, gbase, voff) do { _Pragma("unroll") for (int _i = 0; _i < 2; ++_i) \
;         __builtin_amdgcn_global_load_lds((const unsigned*)((const char*)(gbase) + (voff)[_i]), (LAS unsigned*)(lds + (bufoff) + ldsw + _i * 8192), 16, 0, 0); } while (0)
; #define PG8_LDA(dst, b, h) do { _Pragma("unroll") for (int m = 0; m < 4; ++m) _Pragma("unroll") for (int k = 0; k < 2; ++k) dst[m][k] = *(const LAS bf16x8*)(lds + PG8_SA(b, h) + aoff + m * 2048 + k * 1024); } while (0)
; #define PG8_LDB(dst, b, h) do { _Pragma("unroll") for (int n = 0; n < 2; ++n) _Pragma("unroll") for (int k = 0; k < 2; ++k) dst[n][k] = *(const LAS bf16x8*)(lds + PG8_SB(b, h) + boff + n * 2048 + k * 1024); } while (0)
; #define PG8_MMA(ai, bj, At, Bt) do { __builtin_amdgcn_s_setprio(1); _Pragma("unroll") for (int m = 0; m < 4; ++m) _Pragma("unroll") for (int n = 0; n < 2; ++n) _Pragma("unroll") for (int k = 0; k < 2; ++k) \
;         acc[ai][bj][m][n] = __builtin_amdgcn_mfma_f32_16x16x32_bf16(Bt[n][k], At[m][k], acc[ai][bj][m][n], 0, 0, 0); __builtin_amdgcn_s_setprio(0); } while (0)
; #define PG8_WAIT_V(n) asm volatile("s_waitcnt vmcnt(" #n ")" ::: "memory")
; #define PG8_WAIT_L(n) asm volatile("s_waitcnt lgkmcnt(" #n ")" ::: "memory")
; #define PG8_BAR __builtin_amdgcn_s_barrier()
; #define PG8_SCHED __builtin_amdgcn_sched_barrier(0)
; template <int KK, class Epi, class Sched, bool ALIGN_EPI = true>
; __device__ __forceinline__ void gemm_phase(LAS unsigned char* lds, const bf16* gA, const bf16* gBt, const Sched& S, const Epi& E, const int wid) {
;     ...
;             PG8_LDB(B0, 0, 0); PG8_LDB(B1, 0, 1); PG8_SCHED; PG8_LDA(At, 0, 0); PG8_STAGE(PG8_SA(1, 1), a1 + hstep, voffA);
;             PG8_WAIT_V(8); PG8_WAIT_L(0); PG8_BAR; PG8_MMA(0, 0, At, B0); PG8_MMA(0, 1, At, B1); PG8_BAR; PG8_SCHED;
;             PG8_LDA(At, 0, 1); PG8_STAGE(PG8_SB(0, 0), b2, voffB); PG8_STAGE(PG8_SB(0, 1), b2 + hstep, voffB); PG8_STAGE(PG8_SA(0, 0), a2, voffA);
;             PG8_WAIT_V(8); PG8_WAIT_L(0); PG8_BAR; PG8_MMA(1, 0, At, B0); PG8_MMA(1, 1, At, B1); PG8_BAR; PG8_SCHED;
	s_setprio 1
	s_waitcnt lgkmcnt(0)
	v_mfma_f32_16x16x32_bf16 v[124:127], v[140:143], v[178:181], v[124:127]
	v_mfma_f32_16x16x32_bf16 v[120:123], v[148:151], v[178:181], v[120:123]
	v_mfma_f32_16x16x32_bf16 v[112:115], v[140:143], v[186:189], v[112:115]
	v_mfma_f32_16x16x32_bf16 v[104:107], v[148:151], v[186:189], v[104:107]
	v_mfma_f32_16x16x32_bf16 v[96:99], v[140:143], v[200:203], v[96:99]
	v_mfma_f32_16x16x32_bf16 v[88:91], v[148:151], v[200:203], v[88:91]
	v_mfma_f32_16x16x32_bf16 v[80:83], v[140:143], v[208:211], v[80:83]
	v_mfma_f32_16x16x32_bf16 v[72:75], v[148:151], v[208:211], v[72:75]
	v_mfma_f32_16x16x32_bf16 v[124:127], v[144:147], v[182:185], v[124:127]
	v_mfma_f32_16x16x32_bf16 v[120:123], v[158:161], v[182:185], v[120:123]
	v_mfma_f32_16x16x32_bf16 v[112:115], v[144:147], v[190:193], v[112:115]
	v_mfma_f32_16x16x32_bf16 v[104:107], v[158:161], v[190:193], v[104:107]
	v_mfma_f32_16x16x32_bf16 v[96:99], v[144:147], v[204:207], v[96:99]
	v_mfma_f32_16x16x32_bf16 v[88:91], v[158:161], v[204:207], v[88:91]
	v_mfma_f32_16x16x32_bf16 v[80:83], v[144:147], v[212:215], v[80:83]
	v_mfma_f32_16x16x32_bf16 v[72:75], v[158:161], v[212:215], v[72:75]
	s_setprio 0
	s_setprio 1
	v_mfma_f32_16x16x32_bf16 v[116:119], v[162:165], v[178:181], v[116:119]
	v_mfma_f32_16x16x32_bf16 v[108:111], v[170:173], v[178:181], v[108:111]
	v_mfma_f32_16x16x32_bf16 v[100:103], v[162:165], v[186:189], v[100:103]
	v_mfma_f32_16x16x32_bf16 v[92:95], v[170:173], v[186:189], v[92:95]
	v_mfma_f32_16x16x32_bf16 v[84:87], v[162:165], v[200:203], v[84:87]
	v_mfma_f32_16x16x32_bf16 v[76:79], v[170:173], v[200:203], v[76:79]
	v_mfma_f32_16x16x32_bf16 v[68:71], v[162:165], v[208:211], v[68:71]
	v_mfma_f32_16x16x32_bf16 v[64:67], v[170:173], v[208:211], v[64:67]
	v_mfma_f32_16x16x32_bf16 v[116:119], v[166:169], v[182:185], v[116:119]
	v_mfma_f32_16x16x32_bf16 v[108:111], v[174:177], v[182:185], v[108:111]
	v_mfma_f32_16x16x32_bf16 v[100:103], v[166:169], v[190:193], v[100:103]
	v_mfma_f32_16x16x32_bf16 v[92:95], v[174:177], v[190:193], v[92:95]
	v_mfma_f32_16x16x32_bf16 v[84:87], v[166:169], v[204:207], v[84:87]
	v_mfma_f32_16x16x32_bf16 v[76:79], v[174:177], v[204:207], v[76:79]
	v_mfma_f32_16x16x32_bf16 v[68:71], v[166:169], v[212:215], v[68:71]
	v_mfma_f32_16x16x32_bf16 v[64:67], v[174:177], v[212:215], v[64:67]
	s_setprio 0
	s_barrier
	s_mov_b32 m0, s51
	v_lshl_add_u64 v[194:195], s[52:53], 0, v[130:131]
	s_add_u32 s30, s52, 0xb0000
	ds_read_b128 v[178:181], v154 offset:16384
	ds_read_b128 v[182:185], v154 offset:17408
	ds_read_b128 v[186:189], v154 offset:18432
	ds_read_b128 v[190:193], v154 offset:19456
	ds_read_b128 v[200:203], v154 offset:20480
	ds_read_b128 v[204:207], v154 offset:21504
	ds_read_b128 v[208:211], v154 offset:22528
	ds_read_b128 v[212:215], v154 offset:23552
	global_load_lds_dwordx4 v[194:195], off
	v_lshl_add_u64 v[216:217], s[52:53], 0, v[134:135]
	s_mov_b32 m0, s56
	s_addc_u32 s31, s53, 0
	global_load_lds_dwordx4 v[216:217], off
	v_lshl_add_u64 v[218:219], s[30:31], 0, v[130:131]
	s_mov_b32 m0, s57
	v_lshl_add_u64 v[220:221], s[54:55], 0, v[132:133]
	global_load_lds_dwordx4 v[218:219], off
	v_lshl_add_u64 v[218:219], s[30:31], 0, v[134:135]
	s_mov_b32 m0, s58
	s_nop 0
	global_load_lds_dwordx4 v[218:219], off
	v_lshl_add_u64 v[218:219], s[54:55], 0, v[128:129]
	s_mov_b32 m0, s29
	s_nop 0
	global_load_lds_dwordx4 v[218:219], off
	s_mov_b32 m0, s36
	s_nop 0
	global_load_lds_dwordx4 v[220:221], off
	s_waitcnt vmcnt(8)
	s_waitcnt lgkmcnt(0)
	s_barrier
	s_setprio 1
	s_waitcnt lgkmcnt(0)
	v_mfma_f32_16x16x32_bf16 v[60:63], v[140:143], v[178:181], v[60:63]
	v_mfma_f32_16x16x32_bf16 v[56:59], v[148:151], v[178:181], v[56:59]
	v_mfma_f32_16x16x32_bf16 v[48:51], v[140:143], v[186:189], v[48:51]
	v_mfma_f32_16x16x32_bf16 v[40:43], v[148:151], v[186:189], v[40:43]
	v_mfma_f32_16x16x32_bf16 v[32:35], v[140:143], v[200:203], v[32:35]
	v_mfma_f32_16x16x32_bf16 v[24:27], v[148:151], v[200:203], v[24:27]
	v_mfma_f32_16x16x32_bf16 v[16:19], v[140:143], v[208:211], v[16:19]
	v_mfma_f32_16x16x32_bf16 v[8:11], v[148:151], v[208:211], v[8:11]
	v_mfma_f32_16x16x32_bf16 v[60:63], v[144:147], v[182:185], v[60:63]
	v_mfma_f32_16x16x32_bf16 v[56:59], v[158:161], v[182:185], v[56:59]
	v_mfma_f32_16x16x32_bf16 v[48:51], v[144:147], v[190:193], v[48:51]
	v_mfma_f32_16x16x32_bf16 v[40:43], v[158:161], v[190:193], v[40:43]
	v_mfma_f32_16x16x32_bf16 v[32:35], v[144:147], v[204:207], v[32:35]
	v_mfma_f32_16x16x32_bf16 v[24:27], v[158:161], v[204:207], v[24:27]
	v_mfma_f32_16x16x32_bf16 v[16:19], v[144:147], v[212:215], v[16:19]
	v_mfma_f32_16x16x32_bf16 v[8:11], v[158:161], v[212:215], v[8:11]
	s_setprio 0
	s_setprio 1
	v_mfma_f32_16x16x32_bf16 v[52:55], v[162:165], v[178:181], v[52:55]
	v_mfma_f32_16x16x32_bf16 v[44:47], v[170:173], v[178:181], v[44:47]
	v_mfma_f32_16x16x32_bf16 v[36:39], v[162:165], v[186:189], v[36:39]
	v_mfma_f32_16x16x32_bf16 v[28:31], v[170:173], v[186:189], v[28:31]
	v_mfma_f32_16x16x32_bf16 v[20:23], v[162:165], v[200:203], v[20:23]
	v_mfma_f32_16x16x32_bf16 v[12:15], v[170:173], v[200:203], v[12:15]
	v_mfma_f32_16x16x32_bf16 v[4:7], v[162:165], v[208:211], v[4:7]
	v_mfma_f32_16x16x32_bf16 v[0:3], v[170:173], v[208:211], v[0:3]
	v_mfma_f32_16x16x32_bf16 v[52:55], v[166:169], v[182:185], v[52:55]
	v_mfma_f32_16x16x32_bf16 v[44:47], v[174:177], v[182:185], v[44:47]
	v_mfma_f32_16x16x32_bf16 v[36:39], v[166:169], v[190:193], v[36:39]
	v_mfma_f32_16x16x32_bf16 v[28:31], v[174:177], v[190:193], v[28:31]
	v_mfma_f32_16x16x32_bf16 v[20:23], v[166:169], v[204:207], v[20:23]
	v_mfma_f32_16x16x32_bf16 v[12:15], v[174:177], v[204:207], v[12:15]
	v_mfma_f32_16x16x32_bf16 v[4:7], v[166:169], v[212:215], v[4:7]
	v_mfma_f32_16x16x32_bf16 v[0:3], v[174:177], v[212:215], v[0:3]
	s_setprio 0
	s_barrier
; #define PG8_STAGE(bufoff, gbase, voff) do { _Pragma("unroll") for (int _i = 0; _i < 2; ++_i) \
;         __builtin_amdgcn_global_load_lds((const unsigned*)((const char*)(gbase) + (voff)[_i]), (LAS unsigned*)(lds + (bufoff) + ldsw + _i * 8192), 16, 0, 0); } while (0)
; #define PG8_LDA(dst, b, h) do { _Pragma("unroll") for (int m = 0; m < 4; ++m) _Pragma("unroll") for (int k = 0; k < 2; ++k) dst[m][k] = *(const LAS bf16x8*)(lds + PG8_SA(b, h) + aoff + m * 2048 + k * 1024); } while (0)
; #define PG8_LDB(dst, b, h) do { _Pragma("unroll") for (int n = 0; n < 2; ++n) _Pragma("unroll") for (int k = 0; k < 2; ++k) dst[n][k] = *(const LAS bf16x8*)(lds + PG8_SB(b, h) + boff + n * 2048 + k * 1024); } while (0)
; #define PG8_MMA(ai, bj, At, Bt) do { __builtin_amdgcn_s_setprio(1); _Pragma("unroll") for (int m = 0; m < 4; ++m) _Pragma("unroll") for (int n = 0; n < 2; ++n) _Pragma("unroll") for (int k = 0; k < 2; ++k) \
;         acc[ai][bj][m][n] = __builtin_amdgcn_mfma_f32_16x16x32_bf16(Bt[n][k], At[m][k], acc[ai][bj][m][n], 0, 0, 0); __builtin_amdgcn_s_setprio(0); } while (0)
; #define PG8_WAIT_V(n) asm volatile("s_waitcnt vmcnt(" #n ")" ::: "memory")
; #define PG8_WAIT_L(n) asm volatile("s_waitcnt lgkmcnt(" #n ")" ::: "memory")
; #define PG8_BAR __builtin_amdgcn_s_barrier()
; #define PG8_SCHED __builtin_amdgcn_sched_barrier(0)
; template <int KK, class Epi, class Sched, bool ALIGN_EPI = true>
; __device__ __forceinline__ void gemm_phase(LAS unsigned char* lds, const bf16* gA, const bf16* gBt, const Sched& S, const Epi& E, const int wid) {
;     ...
;             PG8_LDB(B0, 1, 0); PG8_LDB(B1, 1, 1); PG8_SCHED; PG8_LDA(At, 1, 0); PG8_STAGE(PG8_SA(0, 1), a2 + hstep, voffA);
;             PG8_WAIT_V(8); PG8_WAIT_L(0); PG8_BAR; PG8_MMA(0, 0, At, B0); PG8_MMA(0, 1, At, B1); PG8_BAR; PG8_SCHED;
;             PG8_LDA(At, 1, 1); PG8_STAGE(PG8_SB(1, 0), b3, voffB); PG8_STAGE(PG8_SB(1, 1), b3 + hstep, voffB); PG8_STAGE(PG8_SA(1, 0), a3, voffA);
;             PG8_WAIT_V(8); PG8_WAIT_L(0); PG8_BAR; PG8_MMA(1, 0, At, B0); PG8_MMA(1, 1, At, B1); PG8_BAR; PG8_SCHED;
;         }
	ds_read_b128 v[140:143], v155
	ds_read_b128 v[144:147], v155 offset:1024
	ds_read_b128 v[148:151], v155 offset:2048
	ds_read_b128 v[158:161], v155 offset:3072
	ds_read_b128 v[162:165], v156
	ds_read_b128 v[166:169], v156 offset:1024
	ds_read_b128 v[170:173], v156 offset:2048
	ds_read_b128 v[174:177], v156 offset:3072
	s_add_u32 s30, s54, 0xb0000
	s_addc_u32 s31, s55, 0
	s_mov_b32 m0, s37
	v_lshl_add_u64 v[222:223], s[30:31], 0, v[128:129]
	ds_read_b128 v[178:181], v154 offset:32768
	ds_read_b128 v[182:185], v154 offset:33792
	ds_read_b128 v[186:189], v154 offset:34816
	ds_read_b128 v[190:193], v154 offset:35840
	ds_read_b128 v[200:203], v154 offset:36864
	ds_read_b128 v[204:207], v154 offset:37888
	ds_read_b128 v[208:211], v154 offset:38912
	ds_read_b128 v[212:215], v154 offset:39936
	global_load_lds_dwordx4 v[222:223], off
	v_lshl_add_u64 v[222:223], s[30:31], 0, v[132:133]
	s_mov_b32 m0, s38
	s_nop 0
	global_load_lds_dwordx4 v[222:223], off
	s_waitcnt vmcnt(8)
	s_waitcnt lgkmcnt(0)
	s_barrier
	s_setprio 1
	s_waitcnt lgkmcnt(0)
	v_mfma_f32_16x16x32_bf16 v[124:127], v[140:143], v[178:181], v[124:127]
	v_mfma_f32_16x16x32_bf16 v[120:123], v[148:151], v[178:181], v[120:123]
	v_mfma_f32_16x16x32_bf16 v[112:115], v[140:143], v[186:189], v[112:115]
	v_mfma_f32_16x16x32_bf16 v[104:107], v[148:151], v[186:189], v[104:107]
	v_mfma_f32_16x16x32_bf16 v[96:99], v[140:143], v[200:203], v[96:99]
	v_mfma_f32_16x16x32_bf16 v[88:91], v[148:151], v[200:203], v[88:91]
	v_mfma_f32_16x16x32_bf16 v[80:83], v[140:143], v[208:211], v[80:83]
	v_mfma_f32_16x16x32_bf16 v[72:75], v[148:151], v[208:211], v[72:75]
	v_mfma_f32_16x16x32_bf16 v[124:127], v[144:147], v[182:185], v[124:127]
	v_mfma_f32_16x16x32_bf16 v[120:123], v[158:161], v[182:185], v[120:123]
	v_mfma_f32_16x16x32_bf16 v[112:115], v[144:147], v[190:193], v[112:115]
	v_mfma_f32_16x16x32_bf16 v[104:107], v[158:161], v[190:193], v[104:107]
	v_mfma_f32_16x16x32_bf16 v[96:99], v[144:147], v[204:207], v[96:99]
	v_mfma_f32_16x16x32_bf16 v[88:91], v[158:161], v[204:207], v[88:91]
	v_mfma_f32_16x16x32_bf16 v[80:83], v[144:147], v[212:215], v[80:83]
	v_mfma_f32_16x16x32_bf16 v[72:75], v[158:161], v[212:215], v[72:75]
	s_setprio 0
	s_setprio 1
	v_mfma_f32_16x16x32_bf16 v[116:119], v[162:165], v[178:181], v[116:119]
	v_mfma_f32_16x16x32_bf16 v[108:111], v[170:173], v[178:181], v[108:111]
	v_mfma_f32_16x16x32_bf16 v[100:103], v[162:165], v[186:189], v[100:103]
	v_mfma_f32_16x16x32_bf16 v[92:95], v[170:173], v[186:189], v[92:95]
	v_mfma_f32_16x16x32_bf16 v[84:87], v[162:165], v[200:203], v[84:87]
	v_mfma_f32_16x16x32_bf16 v[76:79], v[170:173], v[200:203], v[76:79]
	v_mfma_f32_16x16x32_bf16 v[68:71], v[162:165], v[208:211], v[68:71]
	v_mfma_f32_16x16x32_bf16 v[64:67], v[170:173], v[208:211], v[64:67]
	v_mfma_f32_16x16x32_bf16 v[116:119], v[166:169], v[182:185], v[116:119]
	v_mfma_f32_16x16x32_bf16 v[108:111], v[174:177], v[182:185], v[108:111]
	v_mfma_f32_16x16x32_bf16 v[100:103], v[166:169], v[190:193], v[100:103]
	v_mfma_f32_16x16x32_bf16 v[92:95], v[174:177], v[190:193], v[92:95]
	v_mfma_f32_16x16x32_bf16 v[84:87], v[166:169], v[204:207], v[84:87]
	v_mfma_f32_16x16x32_bf16 v[76:79], v[174:177], v[204:207], v[76:79]
	v_mfma_f32_16x16x32_bf16 v[68:71], v[166:169], v[212:215], v[68:71]
	v_mfma_f32_16x16x32_bf16 v[64:67], v[174:177], v[212:215], v[64:67]
	s_setprio 0
	s_barrier
	s_mov_b32 m0, s59
	v_lshl_add_u64 v[194:195], v[194:195], 0, s[10:11]
	s_add_u32 s30, s52, 0xb0080
	ds_read_b128 v[178:181], v154 offset:49152
	ds_read_b128 v[182:185], v154 offset:50176
	ds_read_b128 v[186:189], v154 offset:51200
	ds_read_b128 v[190:193], v154 offset:52224
	ds_read_b128 v[200:203], v154 offset:53248
	ds_read_b128 v[204:207], v154 offset:54272
	ds_read_b128 v[208:211], v154 offset:55296
	ds_read_b128 v[212:215], v154 offset:56320
	global_load_lds_dwordx4 v[194:195], off
	v_lshl_add_u64 v[194:195], v[216:217], 0, s[10:11]
	s_mov_b32 m0, s60
	s_addc_u32 s31, s53, 0
	global_load_lds_dwordx4 v[194:195], off
	v_lshl_add_u64 v[194:195], s[30:31], 0, v[130:131]
	s_mov_b32 m0, s61
	s_nop 0
	global_load_lds_dwordx4 v[194:195], off
	v_lshl_add_u64 v[194:195], s[30:31], 0, v[134:135]
	s_mov_b32 m0, s62
	s_nop 0
	global_load_lds_dwordx4 v[194:195], off
	v_lshl_add_u64 v[194:195], v[218:219], 0, s[10:11]
	s_mov_b32 m0, s39
	s_nop 0
	global_load_lds_dwordx4 v[194:195], off
	v_lshl_add_u64 v[194:195], v[220:221], 0, s[10:11]
	s_mov_b32 m0, s40
	s_nop 0
	global_load_lds_dwordx4 v[194:195], off
	s_waitcnt vmcnt(8)
	s_waitcnt lgkmcnt(0)
	s_barrier
	s_setprio 1
	s_waitcnt lgkmcnt(0)
	v_mfma_f32_16x16x32_bf16 v[60:63], v[140:143], v[178:181], v[60:63]
	v_mfma_f32_16x16x32_bf16 v[56:59], v[148:151], v[178:181], v[56:59]
	v_mfma_f32_16x16x32_bf16 v[48:51], v[140:143], v[186:189], v[48:51]
	v_mfma_f32_16x16x32_bf16 v[40:43], v[148:151], v[186:189], v[40:43]
	v_mfma_f32_16x16x32_bf16 v[32:35], v[140:143], v[200:203], v[32:35]
	v_mfma_f32_16x16x32_bf16 v[24:27], v[148:151], v[200:203], v[24:27]
	v_mfma_f32_16x16x32_bf16 v[16:19], v[140:143], v[208:211], v[16:19]
	v_mfma_f32_16x16x32_bf16 v[8:11], v[148:151], v[208:211], v[8:11]
	v_mfma_f32_16x16x32_bf16 v[60:63], v[144:147], v[182:185], v[60:63]
	v_mfma_f32_16x16x32_bf16 v[56:59], v[158:161], v[182:185], v[56:59]
	v_mfma_f32_16x16x32_bf16 v[48:51], v[144:147], v[190:193], v[48:51]
	v_mfma_f32_16x16x32_bf16 v[40:43], v[158:161], v[190:193], v[40:43]
	v_mfma_f32_16x16x32_bf16 v[32:35], v[144:147], v[204:207], v[32:35]
	v_mfma_f32_16x16x32_bf16 v[24:27], v[158:161], v[204:207], v[24:27]
	v_mfma_f32_16x16x32_bf16 v[16:19], v[144:147], v[212:215], v[16:19]
	v_mfma_f32_16x16x32_bf16 v[8:11], v[158:161], v[212:215], v[8:11]
	s_setprio 0
	s_setprio 1
	v_mfma_f32_16x16x32_bf16 v[52:55], v[162:165], v[178:181], v[52:55]
	v_mfma_f32_16x16x32_bf16 v[44:47], v[170:173], v[178:181], v[44:47]
	v_mfma_f32_16x16x32_bf16 v[36:39], v[162:165], v[186:189], v[36:39]
	v_mfma_f32_16x16x32_bf16 v[28:31], v[170:173], v[186:189], v[28:31]
	v_mfma_f32_16x16x32_bf16 v[20:23], v[162:165], v[200:203], v[20:23]
	v_mfma_f32_16x16x32_bf16 v[12:15], v[170:173], v[200:203], v[12:15]
	v_mfma_f32_16x16x32_bf16 v[4:7], v[162:165], v[208:211], v[4:7]
	v_mfma_f32_16x16x32_bf16 v[0:3], v[170:173], v[208:211], v[0:3]
	v_mfma_f32_16x16x32_bf16 v[52:55], v[166:169], v[182:185], v[52:55]
	v_mfma_f32_16x16x32_bf16 v[44:47], v[174:177], v[182:185], v[44:47]
	v_mfma_f32_16x16x32_bf16 v[36:39], v[166:169], v[190:193], v[36:39]
	v_mfma_f32_16x16x32_bf16 v[28:31], v[174:177], v[190:193], v[28:31]
	v_mfma_f32_16x16x32_bf16 v[20:23], v[166:169], v[204:207], v[20:23]
	v_mfma_f32_16x16x32_bf16 v[12:15], v[174:177], v[204:207], v[12:15]
	v_mfma_f32_16x16x32_bf16 v[4:7], v[166:169], v[212:215], v[4:7]
	v_mfma_f32_16x16x32_bf16 v[0:3], v[174:177], v[212:215], v[0:3]
	s_setprio 0
	s_barrier
	s_add_i32 s71, s71, 2
	s_add_u32 s69, s69, 0x100
	s_addc_u32 s70, s70, 0
	s_cmp_gt_u32 s71, 41
	s_mov_b64 s[30:31], s[42:43]
	s_cbranch_scc0 .LBB0_671
	s_and_b64 vcc, exec, s[14:15]
	s_cbranch_vccz .LBB0_674
	s_barrier
; #define PG8_BAR __builtin_amdgcn_s_barrier()
; template <int KK, class Epi, class Sched, bool ALIGN_EPI = true>
; __device__ __forceinline__ void gemm_phase(LAS unsigned char* lds, const bf16* gA, const bf16* gBt, const Sched& S, const Epi& E, const int wid) {
;     ...
;         if constexpr (ALIGN_EPI) { if (wr == 0) PG8_BAR; }
;         E(acc, cur, wr, wc, fr, fq);
;         if (!has_next) break;
.LBB0_674:
	s_cmp_lg_u32 s64, 0x100
	s_cbranch_scc1 .Lp5a_epi
	s_cmp_lg_u32 s41, 3
	s_cbranch_scc1 .Lp5a_epi
	s_bfe_u32 s32, s86, 0x20003
	s_and_b32 s90, s86, 7
	s_lshl_b32 s90, s90, 1
	s_bfe_u32 s88, s86, 0x10005
	s_add_i32 s90, s90, s88
	v_readlane_b32 s88, v249, 0
	v_lshlrev_b32_e32 v140, 4, v196
	s_nop 1
	s_lshl_b32 s89, s88, 10
	v_add_u32_e32 v140, s89, v140
	s_mul_i32 s89, s90, 3
	s_lshl_b32 s89, s89, 18
	s_add_u32 s76, s46, s89
	s_addc_u32 s77, s47, 0
	s_add_u32 s76, s76, 0x0
	s_addc_u32 s77, s77, 0
	s_cmp_eq_u32 s32, 0
	s_cbranch_scc1 .Lp5a_cons
	s_add_i32 s89, s32, -1
	s_lshl_b32 s89, s89, 18
	s_add_u32 s76, s76, s89
	s_addc_u32 s77, s77, 0
	s_nop 7
	global_store_dwordx4 v140, v[0:3], s[76:77] sc0 sc1
	s_add_u32 s76, s76, 0x2000
	s_addc_u32 s77, s77, 0
	global_store_dwordx4 v140, v[4:7], s[76:77] sc0 sc1
	s_add_u32 s76, s76, 0x2000
	s_addc_u32 s77, s77, 0
	global_store_dwordx4 v140, v[8:11], s[76:77] sc0 sc1
	s_add_u32 s76, s76, 0x2000
	s_addc_u32 s77, s77, 0
	global_store_dwordx4 v140, v[12:15], s[76:77] sc0 sc1
	s_add_u32 s76, s76, 0x2000
	s_addc_u32 s77, s77, 0
	global_store_dwordx4 v140, v[16:19], s[76:77] sc0 sc1
	s_add_u32 s76, s76, 0x2000
	s_addc_u32 s77, s77, 0
	global_store_dwordx4 v140, v[20:23], s[76:77] sc0 sc1
	s_add_u32 s76, s76, 0x2000
	s_addc_u32 s77, s77, 0
	global_store_dwordx4 v140, v[24:27], s[76:77] sc0 sc1
	s_add_u32 s76, s76, 0x2000
	s_addc_u32 s77, s77, 0
	global_store_dwordx4 v140, v[28:31], s[76:77] sc0 sc1
	s_add_u32 s76, s76, 0x2000
	s_addc_u32 s77, s77, 0
	global_store_dwordx4 v140, v[32:35], s[76:77] sc0 sc1
	s_add_u32 s76, s76, 0x2000
	s_addc_u32 s77, s77, 0
	global_store_dwordx4 v140, v[36:39], s[76:77] sc0 sc1
	s_add_u32 s76, s76, 0x2000
	s_addc_u32 s77, s77, 0
	global_store_dwordx4 v140, v[40:43], s[76:77] sc0 sc1
	s_add_u32 s76, s76, 0x2000
	s_addc_u32 s77, s77, 0
	global_store_dwordx4 v140, v[44:47], s[76:77] sc0 sc1
	s_add_u32 s76, s76, 0x2000
	s_addc_u32 s77, s77, 0
	global_store_dwordx4 v140, v[48:51], s[76:77] sc0 sc1
	s_add_u32 s76, s76, 0x2000
	s_addc_u32 s77, s77, 0
	global_store_dwordx4 v140, v[52:55], s[76:77] sc0 sc1
	s_add_u32 s76, s76, 0x2000
	s_addc_u32 s77, s77, 0
	global_store_dwordx4 v140, v[56:59], s[76:77] sc0 sc1
	s_add_u32 s76, s76, 0x2000
	s_addc_u32 s77, s77, 0
	global_store_dwordx4 v140, v[60:63], s[76:77] sc0 sc1
	s_add_u32 s76, s76, 0x2000
	s_addc_u32 s77, s77, 0
	global_store_dwordx4 v140, v[64:67], s[76:77] sc0 sc1
	s_add_u32 s76, s76, 0x2000
	s_addc_u32 s77, s77, 0
	global_store_dwordx4 v140, v[68:71], s[76:77] sc0 sc1
	s_add_u32 s76, s76, 0x2000
	s_addc_u32 s77, s77, 0
	global_store_dwordx4 v140, v[72:75], s[76:77] sc0 sc1
	s_add_u32 s76, s76, 0x2000
	s_addc_u32 s77, s77, 0
	global_store_dwordx4 v140, v[76:79], s[76:77] sc0 sc1
	s_add_u32 s76, s76, 0x2000
	s_addc_u32 s77, s77, 0
	global_store_dwordx4 v140, v[80:83], s[76:77] sc0 sc1
	s_add_u32 s76, s76, 0x2000
	s_addc_u32 s77, s77, 0
	global_store_dwordx4 v140, v[84:87], s[76:77] sc0 sc1
	s_add_u32 s76, s76, 0x2000
	s_addc_u32 s77, s77, 0
	global_store_dwordx4 v140, v[88:91], s[76:77] sc0 sc1
	s_add_u32 s76, s76, 0x2000
	s_addc_u32 s77, s77, 0
	global_store_dwordx4 v140, v[92:95], s[76:77] sc0 sc1
	s_add_u32 s76, s76, 0x2000
	s_addc_u32 s77, s77, 0
	global_store_dwordx4 v140, v[96:99], s[76:77] sc0 sc1
	s_add_u32 s76, s76, 0x2000
	s_addc_u32 s77, s77, 0
	global_store_dwordx4 v140, v[100:103], s[76:77] sc0 sc1
	s_add_u32 s76, s76, 0x2000
	s_addc_u32 s77, s77, 0
	global_store_dwordx4 v140, v[104:107], s[76:77] sc0 sc1
	s_add_u32 s76, s76, 0x2000
	s_addc_u32 s77, s77, 0
	global_store_dwordx4 v140, v[108:111], s[76:77] sc0 sc1
	s_add_u32 s76, s76, 0x2000
	s_addc_u32 s77, s77, 0
	global_store_dwordx4 v140, v[112:115], s[76:77] sc0 sc1
	s_add_u32 s76, s76, 0x2000
	s_addc_u32 s77, s77, 0
	global_store_dwordx4 v140, v[116:119], s[76:77] sc0 sc1
	s_add_u32 s76, s76, 0x2000
	s_addc_u32 s77, s77, 0
	global_store_dwordx4 v140, v[120:123], s[76:77] sc0 sc1
	s_add_u32 s76, s76, 0x2000
	s_addc_u32 s77, s77, 0
	global_store_dwordx4 v140, v[124:127], s[76:77] sc0 sc1
	s_waitcnt vmcnt(0)
	s_lshl_b32 s89, s90, 2
	s_add_i32 s89, s89, s32
	s_lshl_b32 s89, s89, 2
	v_mov_b32_e32 v141, s89
	v_mov_b32_e32 v142, 1
	s_mov_b64 s[78:79], exec
	s_mov_b64 exec, 1
	global_atomic_add v141, v142, s[44:45] offset:3200
	s_mov_b64 exec, s[78:79]
	s_branch .LBB0_677
.Lp5a_cons:
	s_lshl_b32 s89, s90, 4
	v_mov_b32_e32 v141, s89
.Lp5a_poll2:
	global_load_dword v142, v141, s[44:45] offset:3208 sc1
	s_waitcnt vmcnt(0)
	v_readfirstlane_b32 s82, v142
	s_nop 0
	s_cmp_ge_u32 s82, 8
	s_cbranch_scc1 .Lp5a_go2
	s_sleep 1
	s_branch .Lp5a_poll2
; #define PG8_BAR __builtin_amdgcn_s_barrier()
; template <int KK, class Epi, class Sched, bool ALIGN_EPI = true>
; __device__ __forceinline__ void gemm_phase(LAS unsigned char* lds, const bf16* gA, const bf16* gBt, const Sched& S, const Epi& E, const int wid) {
;     ...
;         if constexpr (ALIGN_EPI) { if (wr == 0) PG8_BAR; }
;         E(acc, cur, wr, wc, fr, fq);
.Lp5a_go2:
	s_add_u32 s78, s76, 0x40000
	s_addc_u32 s79, s77, 0
	global_load_dwordx4 v[200:203], v140, s[78:79] sc0 sc1
	s_add_u32 s78, s78, 0x2000
	s_addc_u32 s79, s79, 0
	global_load_dwordx4 v[204:207], v140, s[78:79] sc0 sc1
	s_add_u32 s78, s78, 0x2000
	s_addc_u32 s79, s79, 0
	global_load_dwordx4 v[208:211], v140, s[78:79] sc0 sc1
	s_add_u32 s78, s78, 0x2000
	s_addc_u32 s79, s79, 0
	global_load_dwordx4 v[212:215], v140, s[78:79] sc0 sc1
	s_add_u32 s78, s78, 0x2000
	s_addc_u32 s79, s79, 0
	global_load_dwordx4 v[216:219], v140, s[78:79] sc0 sc1
	s_add_u32 s78, s78, 0x2000
	s_addc_u32 s79, s79, 0
	global_load_dwordx4 v[220:223], v140, s[78:79] sc0 sc1
	s_add_u32 s78, s78, 0x2000
	s_addc_u32 s79, s79, 0
	global_load_dwordx4 v[224:227], v140, s[78:79] sc0 sc1
	s_add_u32 s78, s78, 0x2000
	s_addc_u32 s79, s79, 0
	global_load_dwordx4 v[228:231], v140, s[78:79] sc0 sc1
	s_add_u32 s78, s78, 0x2000
	s_addc_u32 s79, s79, 0
	global_load_dwordx4 v[232:235], v140, s[78:79] sc0 sc1
	s_add_u32 s78, s78, 0x2000
	s_addc_u32 s79, s79, 0
	global_load_dwordx4 v[236:239], v140, s[78:79] sc0 sc1
	s_add_u32 s78, s78, 0x2000
	s_addc_u32 s79, s79, 0
	global_load_dwordx4 v[240:243], v140, s[78:79] sc0 sc1
	s_add_u32 s78, s78, 0x2000
	s_addc_u32 s79, s79, 0
	global_load_dwordx4 v[244:247], v140, s[78:79] sc0 sc1
	s_add_u32 s78, s78, 0x2000
	s_addc_u32 s79, s79, 0
	global_load_dwordx4 v[160:163], v140, s[78:79] sc0 sc1
	s_add_u32 s78, s78, 0x2000
	s_addc_u32 s79, s79, 0
	global_load_dwordx4 v[164:167], v140, s[78:79] sc0 sc1
	s_add_u32 s78, s78, 0x2000
	s_addc_u32 s79, s79, 0
	global_load_dwordx4 v[168:171], v140, s[78:79] sc0 sc1
	s_add_u32 s78, s78, 0x2000
	s_addc_u32 s79, s79, 0
	global_load_dwordx4 v[172:175], v140, s[78:79] sc0 sc1
	s_add_u32 s78, s78, 0x2000
	s_addc_u32 s79, s79, 0
	s_waitcnt vmcnt(15)
	v_pk_add_f32 v[0:1], v[0:1], v[200:201]
	v_pk_add_f32 v[2:3], v[2:3], v[202:203]
	s_waitcnt vmcnt(14)
	v_pk_add_f32 v[4:5], v[4:5], v[204:205]
	v_pk_add_f32 v[6:7], v[6:7], v[206:207]
	s_waitcnt vmcnt(13)
	v_pk_add_f32 v[8:9], v[8:9], v[208:209]
	v_pk_add_f32 v[10:11], v[10:11], v[210:211]
	s_waitcnt vmcnt(12)
	v_pk_add_f32 v[12:13], v[12:13], v[212:213]
	v_pk_add_f32 v[14:15], v[14:15], v[214:215]
	s_waitcnt vmcnt(11)
	v_pk_add_f32 v[16:17], v[16:17], v[216:217]
	v_pk_add_f32 v[18:19], v[18:19], v[218:219]
	s_waitcnt vmcnt(10)
	v_pk_add_f32 v[20:21], v[20:21], v[220:221]
	v_pk_add_f32 v[22:23], v[22:23], v[222:223]
	s_waitcnt vmcnt(9)
	v_pk_add_f32 v[24:25], v[24:25], v[224:225]
	v_pk_add_f32 v[26:27], v[26:27], v[226:227]
	s_waitcnt vmcnt(8)
	v_pk_add_f32 v[28:29], v[28:29], v[228:229]
	v_pk_add_f32 v[30:31], v[30:31], v[230:231]
	s_waitcnt vmcnt(7)
	v_pk_add_f32 v[32:33], v[32:33], v[232:233]
	v_pk_add_f32 v[34:35], v[34:35], v[234:235]
	s_waitcnt vmcnt(6)
	v_pk_add_f32 v[36:37], v[36:37], v[236:237]
	v_pk_add_f32 v[38:39], v[38:39], v[238:239]
	s_waitcnt vmcnt(5)
	v_pk_add_f32 v[40:41], v[40:41], v[240:241]
	v_pk_add_f32 v[42:43], v[42:43], v[242:243]
	s_waitcnt vmcnt(4)
	v_pk_add_f32 v[44:45], v[44:45], v[244:245]
	v_pk_add_f32 v[46:47], v[46:47], v[246:247]
	s_waitcnt vmcnt(3)
	v_pk_add_f32 v[48:49], v[48:49], v[160:161]
	v_pk_add_f32 v[50:51], v[50:51], v[162:163]
	s_waitcnt vmcnt(2)
	v_pk_add_f32 v[52:53], v[52:53], v[164:165]
	v_pk_add_f32 v[54:55], v[54:55], v[166:167]
	s_waitcnt vmcnt(1)
	v_pk_add_f32 v[56:57], v[56:57], v[168:169]
	v_pk_add_f32 v[58:59], v[58:59], v[170:171]
	s_waitcnt vmcnt(0)
	v_pk_add_f32 v[60:61], v[60:61], v[172:173]
	v_pk_add_f32 v[62:63], v[62:63], v[174:175]
	global_load_dwordx4 v[200:203], v140, s[78:79] sc0 sc1
	s_add_u32 s78, s78, 0x2000
	s_addc_u32 s79, s79, 0
	global_load_dwordx4 v[204:207], v140, s[78:79] sc0 sc1
	s_add_u32 s78, s78, 0x2000
	s_addc_u32 s79, s79, 0
	global_load_dwordx4 v[208:211], v140, s[78:79] sc0 sc1
	s_add_u32 s78, s78, 0x2000
	s_addc_u32 s79, s79, 0
	global_load_dwordx4 v[212:215], v140, s[78:79] sc0 sc1
	s_add_u32 s78, s78, 0x2000
	s_addc_u32 s79, s79, 0
	global_load_dwordx4 v[216:219], v140, s[78:79] sc0 sc1
	s_add_u32 s78, s78, 0x2000
	s_addc_u32 s79, s79, 0
	global_load_dwordx4 v[220:223], v140, s[78:79] sc0 sc1
	s_add_u32 s78, s78, 0x2000
	s_addc_u32 s79, s79, 0
	global_load_dwordx4 v[224:227], v140, s[78:79] sc0 sc1
	s_add_u32 s78, s78, 0x2000
	s_addc_u32 s79, s79, 0
	global_load_dwordx4 v[228:231], v140, s[78:79] sc0 sc1
	s_add_u32 s78, s78, 0x2000
	s_addc_u32 s79, s79, 0
	global_load_dwordx4 v[232:235], v140, s[78:79] sc0 sc1
	s_add_u32 s78, s78, 0x2000
	s_addc_u32 s79, s79, 0
	global_load_dwordx4 v[236:239], v140, s[78:79] sc0 sc1
	s_add_u32 s78, s78, 0x2000
	s_addc_u32 s79, s79, 0
	global_load_dwordx4 v[240:243], v140, s[78:79] sc0 sc1
	s_add_u32 s78, s78, 0x2000
	s_addc_u32 s79, s79, 0
	global_load_dwordx4 v[244:247], v140, s[78:79] sc0 sc1
	s_add_u32 s78, s78, 0x2000
	s_addc_u32 s79, s79, 0
	global_load_dwordx4 v[160:163], v140, s[78:79] sc0 sc1
	s_add_u32 s78, s78, 0x2000
	s_addc_u32 s79, s79, 0
	global_load_dwordx4 v[164:167], v140, s[78:79] sc0 sc1
	s_add_u32 s78, s78, 0x2000
	s_addc_u32 s79, s79, 0
	global_load_dwordx4 v[168:171], v140, s[78:79] sc0 sc1
	s_add_u32 s78, s78, 0x2000
	s_addc_u32 s79, s79, 0
	global_load_dwordx4 v[172:175], v140, s[78:79] sc0 sc1
	s_add_u32 s78, s78, 0x2000
	s_addc_u32 s79, s79, 0
	s_waitcnt vmcnt(15)
	v_pk_add_f32 v[64:65], v[64:65], v[200:201]
	v_pk_add_f32 v[66:67], v[66:67], v[202:203]
	s_waitcnt vmcnt(14)
	v_pk_add_f32 v[68:69], v[68:69], v[204:205]
	v_pk_add_f32 v[70:71], v[70:71], v[206:207]
	s_waitcnt vmcnt(13)
	v_pk_add_f32 v[72:73], v[72:73], v[208:209]
	v_pk_add_f32 v[74:75], v[74:75], v[210:211]
	s_waitcnt vmcnt(12)
; #define PG8_BAR __builtin_amdgcn_s_barrier()
; template <int KK, class Epi, class Sched, bool ALIGN_EPI = true>
; __device__ __forceinline__ void gemm_phase(LAS unsigned char* lds, const bf16* gA, const bf16* gBt, const Sched& S, const Epi& E, const int wid) {
;     ...
;         if constexpr (ALIGN_EPI) { if (wr == 0) PG8_BAR; }
;         E(acc, cur, wr, wc, fr, fq);
	v_pk_add_f32 v[76:77], v[76:77], v[212:213]
	v_pk_add_f32 v[78:79], v[78:79], v[214:215]
	s_waitcnt vmcnt(11)
	v_pk_add_f32 v[80:81], v[80:81], v[216:217]
	v_pk_add_f32 v[82:83], v[82:83], v[218:219]
	s_waitcnt vmcnt(10)
	v_pk_add_f32 v[84:85], v[84:85], v[220:221]
	v_pk_add_f32 v[86:87], v[86:87], v[222:223]
	s_waitcnt vmcnt(9)
	v_pk_add_f32 v[88:89], v[88:89], v[224:225]
	v_pk_add_f32 v[90:91], v[90:91], v[226:227]
	s_waitcnt vmcnt(8)
	v_pk_add_f32 v[92:93], v[92:93], v[228:229]
	v_pk_add_f32 v[94:95], v[94:95], v[230:231]
	s_waitcnt vmcnt(7)
	v_pk_add_f32 v[96:97], v[96:97], v[232:233]
	v_pk_add_f32 v[98:99], v[98:99], v[234:235]
	s_waitcnt vmcnt(6)
	v_pk_add_f32 v[100:101], v[100:101], v[236:237]
	v_pk_add_f32 v[102:103], v[102:103], v[238:239]
	s_waitcnt vmcnt(5)
	v_pk_add_f32 v[104:105], v[104:105], v[240:241]
	v_pk_add_f32 v[106:107], v[106:107], v[242:243]
	s_waitcnt vmcnt(4)
	v_pk_add_f32 v[108:109], v[108:109], v[244:245]
	v_pk_add_f32 v[110:111], v[110:111], v[246:247]
	s_waitcnt vmcnt(3)
	v_pk_add_f32 v[112:113], v[112:113], v[160:161]
	v_pk_add_f32 v[114:115], v[114:115], v[162:163]
	s_waitcnt vmcnt(2)
	v_pk_add_f32 v[116:117], v[116:117], v[164:165]
	v_pk_add_f32 v[118:119], v[118:119], v[166:167]
	s_waitcnt vmcnt(1)
	v_pk_add_f32 v[120:121], v[120:121], v[168:169]
	v_pk_add_f32 v[122:123], v[122:123], v[170:171]
	s_waitcnt vmcnt(0)
	v_pk_add_f32 v[124:125], v[124:125], v[172:173]
	v_pk_add_f32 v[126:127], v[126:127], v[174:175]
.Lp5a_poll3:
	global_load_dword v142, v141, s[44:45] offset:3212 sc1
	s_waitcnt vmcnt(0)
	v_readfirstlane_b32 s82, v142
	s_nop 0
	s_cmp_ge_u32 s82, 8
	s_cbranch_scc1 .Lp5a_go3
	s_sleep 1
	s_branch .Lp5a_poll3
.Lp5a_go3:
	s_add_u32 s78, s76, 0x80000
	s_addc_u32 s79, s77, 0
	global_load_dwordx4 v[200:203], v140, s[78:79] sc0 sc1
	s_add_u32 s78, s78, 0x2000
	s_addc_u32 s79, s79, 0
	global_load_dwordx4 v[204:207], v140, s[78:79] sc0 sc1
	s_add_u32 s78, s78, 0x2000
	s_addc_u32 s79, s79, 0
	global_load_dwordx4 v[208:211], v140, s[78:79] sc0 sc1
	s_add_u32 s78, s78, 0x2000
	s_addc_u32 s79, s79, 0
	global_load_dwordx4 v[212:215], v140, s[78:79] sc0 sc1
	s_add_u32 s78, s78, 0x2000
	s_addc_u32 s79, s79, 0
	global_load_dwordx4 v[216:219], v140, s[78:79] sc0 sc1
	s_add_u32 s78, s78, 0x2000
	s_addc_u32 s79, s79, 0
	global_load_dwordx4 v[220:223], v140, s[78:79] sc0 sc1
	s_add_u32 s78, s78, 0x2000
	s_addc_u32 s79, s79, 0
	global_load_dwordx4 v[224:227], v140, s[78:79] sc0 sc1
	s_add_u32 s78, s78, 0x2000
	s_addc_u32 s79, s79, 0
	global_load_dwordx4 v[228:231], v140, s[78:79] sc0 sc1
	s_add_u32 s78, s78, 0x2000
	s_addc_u32 s79, s79, 0
	global_load_dwordx4 v[232:235], v140, s[78:79] sc0 sc1
	s_add_u32 s78, s78, 0x2000
	s_addc_u32 s79, s79, 0
	global_load_dwordx4 v[236:239], v140, s[78:79] sc0 sc1
	s_add_u32 s78, s78, 0x2000
	s_addc_u32 s79, s79, 0
	global_load_dwordx4 v[240:243], v140, s[78:79] sc0 sc1
	s_add_u32 s78, s78, 0x2000
	s_addc_u32 s79, s79, 0
	global_load_dwordx4 v[244:247], v140, s[78:79] sc0 sc1
	s_add_u32 s78, s78, 0x2000
	s_addc_u32 s79, s79, 0
	global_load_dwordx4 v[160:163], v140, s[78:79] sc0 sc1
	s_add_u32 s78, s78, 0x2000
	s_addc_u32 s79, s79, 0
	global_load_dwordx4 v[164:167], v140, s[78:79] sc0 sc1
	s_add_u32 s78, s78, 0x2000
	s_addc_u32 s79, s79, 0
	global_load_dwordx4 v[168:171], v140, s[78:79] sc0 sc1
	s_add_u32 s78, s78, 0x2000
	s_addc_u32 s79, s79, 0
	global_load_dwordx4 v[172:175], v140, s[78:79] sc0 sc1
	s_add_u32 s78, s78, 0x2000
	s_addc_u32 s79, s79, 0
	s_waitcnt vmcnt(15)
	v_pk_add_f32 v[0:1], v[0:1], v[200:201]
	v_pk_add_f32 v[2:3], v[2:3], v[202:203]
	s_waitcnt vmcnt(14)
	v_pk_add_f32 v[4:5], v[4:5], v[204:205]
	v_pk_add_f32 v[6:7], v[6:7], v[206:207]
	s_waitcnt vmcnt(13)
	v_pk_add_f32 v[8:9], v[8:9], v[208:209]
	v_pk_add_f32 v[10:11], v[10:11], v[210:211]
	s_waitcnt vmcnt(12)
	v_pk_add_f32 v[12:13], v[12:13], v[212:213]
	v_pk_add_f32 v[14:15], v[14:15], v[214:215]
	s_waitcnt vmcnt(11)
	v_pk_add_f32 v[16:17], v[16:17], v[216:217]
	v_pk_add_f32 v[18:19], v[18:19], v[218:219]
	s_waitcnt vmcnt(10)
	v_pk_add_f32 v[20:21], v[20:21], v[220:221]
	v_pk_add_f32 v[22:23], v[22:23], v[222:223]
	s_waitcnt vmcnt(9)
	v_pk_add_f32 v[24:25], v[24:25], v[224:225]
	v_pk_add_f32 v[26:27], v[26:27], v[226:227]
	s_waitcnt vmcnt(8)
	v_pk_add_f32 v[28:29], v[28:29], v[228:229]
	v_pk_add_f32 v[30:31], v[30:31], v[230:231]
	s_waitcnt vmcnt(7)
	v_pk_add_f32 v[32:33], v[32:33], v[232:233]
	v_pk_add_f32 v[34:35], v[34:35], v[234:235]
	s_waitcnt vmcnt(6)
	v_pk_add_f32 v[36:37], v[36:37], v[236:237]
	v_pk_add_f32 v[38:39], v[38:39], v[238:239]
	s_waitcnt vmcnt(5)
	v_pk_add_f32 v[40:41], v[40:41], v[240:241]
	v_pk_add_f32 v[42:43], v[42:43], v[242:243]
	s_waitcnt vmcnt(4)
	v_pk_add_f32 v[44:45], v[44:45], v[244:245]
	v_pk_add_f32 v[46:47], v[46:47], v[246:247]
	s_waitcnt vmcnt(3)
	v_pk_add_f32 v[48:49], v[48:49], v[160:161]
	v_pk_add_f32 v[50:51], v[50:51], v[162:163]
	s_waitcnt vmcnt(2)
	v_pk_add_f32 v[52:53], v[52:53], v[164:165]
	v_pk_add_f32 v[54:55], v[54:55], v[166:167]
	s_waitcnt vmcnt(1)
	v_pk_add_f32 v[56:57], v[56:57], v[168:169]
	v_pk_add_f32 v[58:59], v[58:59], v[170:171]
	s_waitcnt vmcnt(0)
; #define PG8_BAR __builtin_amdgcn_s_barrier()
; template <int KK, class Epi, class Sched, bool ALIGN_EPI = true>
; __device__ __forceinline__ void gemm_phase(LAS unsigned char* lds, const bf16* gA, const bf16* gBt, const Sched& S, const Epi& E, const int wid) {
;     ...
;         if constexpr (ALIGN_EPI) { if (wr == 0) PG8_BAR; }
;         E(acc, cur, wr, wc, fr, fq);
	v_pk_add_f32 v[60:61], v[60:61], v[172:173]
	v_pk_add_f32 v[62:63], v[62:63], v[174:175]
	global_load_dwordx4 v[200:203], v140, s[78:79] sc0 sc1
	s_add_u32 s78, s78, 0x2000
	s_addc_u32 s79, s79, 0
	global_load_dwordx4 v[204:207], v140, s[78:79] sc0 sc1
	s_add_u32 s78, s78, 0x2000
	s_addc_u32 s79, s79, 0
	global_load_dwordx4 v[208:211], v140, s[78:79] sc0 sc1
	s_add_u32 s78, s78, 0x2000
	s_addc_u32 s79, s79, 0
	global_load_dwordx4 v[212:215], v140, s[78:79] sc0 sc1
	s_add_u32 s78, s78, 0x2000
	s_addc_u32 s79, s79, 0
	global_load_dwordx4 v[216:219], v140, s[78:79] sc0 sc1
	s_add_u32 s78, s78, 0x2000
	s_addc_u32 s79, s79, 0
	global_load_dwordx4 v[220:223], v140, s[78:79] sc0 sc1
	s_add_u32 s78, s78, 0x2000
	s_addc_u32 s79, s79, 0
	global_load_dwordx4 v[224:227], v140, s[78:79] sc0 sc1
	s_add_u32 s78, s78, 0x2000
	s_addc_u32 s79, s79, 0
	global_load_dwordx4 v[228:231], v140, s[78:79] sc0 sc1
	s_add_u32 s78, s78, 0x2000
	s_addc_u32 s79, s79, 0
	global_load_dwordx4 v[232:235], v140, s[78:79] sc0 sc1
	s_add_u32 s78, s78, 0x2000
	s_addc_u32 s79, s79, 0
	global_load_dwordx4 v[236:239], v140, s[78:79] sc0 sc1
	s_add_u32 s78, s78, 0x2000
	s_addc_u32 s79, s79, 0
	global_load_dwordx4 v[240:243], v140, s[78:79] sc0 sc1
	s_add_u32 s78, s78, 0x2000
	s_addc_u32 s79, s79, 0
	global_load_dwordx4 v[244:247], v140, s[78:79] sc0 sc1
	s_add_u32 s78, s78, 0x2000
	s_addc_u32 s79, s79, 0
	global_load_dwordx4 v[160:163], v140, s[78:79] sc0 sc1
	s_add_u32 s78, s78, 0x2000
	s_addc_u32 s79, s79, 0
	global_load_dwordx4 v[164:167], v140, s[78:79] sc0 sc1
	s_add_u32 s78, s78, 0x2000
	s_addc_u32 s79, s79, 0
	global_load_dwordx4 v[168:171], v140, s[78:79] sc0 sc1
	s_add_u32 s78, s78, 0x2000
	s_addc_u32 s79, s79, 0
	global_load_dwordx4 v[172:175], v140, s[78:79] sc0 sc1
	s_add_u32 s78, s78, 0x2000
	s_addc_u32 s79, s79, 0
	s_waitcnt vmcnt(15)
	v_pk_add_f32 v[64:65], v[64:65], v[200:201]
	v_pk_add_f32 v[66:67], v[66:67], v[202:203]
	s_waitcnt vmcnt(14)
	v_pk_add_f32 v[68:69], v[68:69], v[204:205]
	v_pk_add_f32 v[70:71], v[70:71], v[206:207]
	s_waitcnt vmcnt(13)
	v_pk_add_f32 v[72:73], v[72:73], v[208:209]
	v_pk_add_f32 v[74:75], v[74:75], v[210:211]
	s_waitcnt vmcnt(12)
	v_pk_add_f32 v[76:77], v[76:77], v[212:213]
	v_pk_add_f32 v[78:79], v[78:79], v[214:215]
	s_waitcnt vmcnt(11)
	v_pk_add_f32 v[80:81], v[80:81], v[216:217]
	v_pk_add_f32 v[82:83], v[82:83], v[218:219]
	s_waitcnt vmcnt(10)
	v_pk_add_f32 v[84:85], v[84:85], v[220:221]
	v_pk_add_f32 v[86:87], v[86:87], v[222:223]
	s_waitcnt vmcnt(9)
	v_pk_add_f32 v[88:89], v[88:89], v[224:225]
	v_pk_add_f32 v[90:91], v[90:91], v[226:227]
	s_waitcnt vmcnt(8)
	v_pk_add_f32 v[92:93], v[92:93], v[228:229]
	v_pk_add_f32 v[94:95], v[94:95], v[230:231]
	s_waitcnt vmcnt(7)
	v_pk_add_f32 v[96:97], v[96:97], v[232:233]
	v_pk_add_f32 v[98:99], v[98:99], v[234:235]
	s_waitcnt vmcnt(6)
	v_pk_add_f32 v[100:101], v[100:101], v[236:237]
	v_pk_add_f32 v[102:103], v[102:103], v[238:239]
	s_waitcnt vmcnt(5)
	v_pk_add_f32 v[104:105], v[104:105], v[240:241]
	v_pk_add_f32 v[106:107], v[106:107], v[242:243]
	s_waitcnt vmcnt(4)
	v_pk_add_f32 v[108:109], v[108:109], v[244:245]
	v_pk_add_f32 v[110:111], v[110:111], v[246:247]
	s_waitcnt vmcnt(3)
	v_pk_add_f32 v[112:113], v[112:113], v[160:161]
	v_pk_add_f32 v[114:115], v[114:115], v[162:163]
	s_waitcnt vmcnt(2)
	v_pk_add_f32 v[116:117], v[116:117], v[164:165]
	v_pk_add_f32 v[118:119], v[118:119], v[166:167]
	s_waitcnt vmcnt(1)
	v_pk_add_f32 v[120:121], v[120:121], v[168:169]
	v_pk_add_f32 v[122:123], v[122:123], v[170:171]
	s_waitcnt vmcnt(0)
	v_pk_add_f32 v[124:125], v[124:125], v[172:173]
	v_pk_add_f32 v[126:127], v[126:127], v[174:175]
.Lp5a_poll1:
	global_load_dword v142, v141, s[44:45] offset:3204 sc1
	s_waitcnt vmcnt(0)
	v_readfirstlane_b32 s82, v142
	s_nop 0
	s_cmp_ge_u32 s82, 8
	s_cbranch_scc1 .Lp5a_go1
	s_sleep 1
	s_branch .Lp5a_poll1
.Lp5a_go1:
	s_add_u32 s78, s76, 0x0
	s_addc_u32 s79, s77, 0
	global_load_dwordx4 v[200:203], v140, s[78:79] sc0 sc1
	s_add_u32 s78, s78, 0x2000
	s_addc_u32 s79, s79, 0
	global_load_dwordx4 v[204:207], v140, s[78:79] sc0 sc1
	s_add_u32 s78, s78, 0x2000
	s_addc_u32 s79, s79, 0
	global_load_dwordx4 v[208:211], v140, s[78:79] sc0 sc1
	s_add_u32 s78, s78, 0x2000
	s_addc_u32 s79, s79, 0
	global_load_dwordx4 v[212:215], v140, s[78:79] sc0 sc1
	s_add_u32 s78, s78, 0x2000
	s_addc_u32 s79, s79, 0
	global_load_dwordx4 v[216:219], v140, s[78:79] sc0 sc1
	s_add_u32 s78, s78, 0x2000
	s_addc_u32 s79, s79, 0
	global_load_dwordx4 v[220:223], v140, s[78:79] sc0 sc1
	s_add_u32 s78, s78, 0x2000
	s_addc_u32 s79, s79, 0
	global_load_dwordx4 v[224:227], v140, s[78:79] sc0 sc1
	s_add_u32 s78, s78, 0x2000
	s_addc_u32 s79, s79, 0
	global_load_dwordx4 v[228:231], v140, s[78:79] sc0 sc1
	s_add_u32 s78, s78, 0x2000
	s_addc_u32 s79, s79, 0
	global_load_dwordx4 v[232:235], v140, s[78:79] sc0 sc1
	s_add_u32 s78, s78, 0x2000
	s_addc_u32 s79, s79, 0
	global_load_dwordx4 v[236:239], v140, s[78:79] sc0 sc1
	s_add_u32 s78, s78, 0x2000
	s_addc_u32 s79, s79, 0
	global_load_dwordx4 v[240:243], v140, s[78:79] sc0 sc1
	s_add_u32 s78, s78, 0x2000
	s_addc_u32 s79, s79, 0
	global_load_dwordx4 v[244:247], v140, s[78:79] sc0 sc1
	s_add_u32 s78, s78, 0x2000
	s_addc_u32 s79, s79, 0
	global_load_dwordx4 v[160:163], v140, s[78:79] sc0 sc1
	s_add_u32 s78, s78, 0x2000
	s_addc_u32 s79, s79, 0
	global_load_dwordx4 v[164:167], v140, s[78:79] sc0 sc1
	s_add_u32 s78, s78, 0x2000
	s_addc_u32 s79, s79, 0
	global_load_dwordx4 v[168:171], v140, s[78:79] sc0 sc1
	s_add_u32 s78, s78, 0x2000
	s_addc_u32 s79, s79, 0
	global_load_dwordx4 v[172:175], v140, s[78:79] sc0 sc1
	s_add_u32 s78, s78, 0x2000
	s_addc_u32 s79, s79, 0
	s_waitcnt vmcnt(15)
; #define PG8_BAR __builtin_amdgcn_s_barrier()
; template <int KK, class Epi, class Sched, bool ALIGN_EPI = true>
; __device__ __forceinline__ void gemm_phase(LAS unsigned char* lds, const bf16* gA, const bf16* gBt, const Sched& S, const Epi& E, const int wid) {
;     ...
;         if constexpr (ALIGN_EPI) { if (wr == 0) PG8_BAR; }
;         E(acc, cur, wr, wc, fr, fq);
	v_pk_add_f32 v[0:1], v[0:1], v[200:201]
	v_pk_add_f32 v[2:3], v[2:3], v[202:203]
	s_waitcnt vmcnt(14)
	v_pk_add_f32 v[4:5], v[4:5], v[204:205]
	v_pk_add_f32 v[6:7], v[6:7], v[206:207]
	s_waitcnt vmcnt(13)
	v_pk_add_f32 v[8:9], v[8:9], v[208:209]
	v_pk_add_f32 v[10:11], v[10:11], v[210:211]
	s_waitcnt vmcnt(12)
	v_pk_add_f32 v[12:13], v[12:13], v[212:213]
	v_pk_add_f32 v[14:15], v[14:15], v[214:215]
	s_waitcnt vmcnt(11)
	v_pk_add_f32 v[16:17], v[16:17], v[216:217]
	v_pk_add_f32 v[18:19], v[18:19], v[218:219]
	s_waitcnt vmcnt(10)
	v_pk_add_f32 v[20:21], v[20:21], v[220:221]
	v_pk_add_f32 v[22:23], v[22:23], v[222:223]
	s_waitcnt vmcnt(9)
	v_pk_add_f32 v[24:25], v[24:25], v[224:225]
	v_pk_add_f32 v[26:27], v[26:27], v[226:227]
	s_waitcnt vmcnt(8)
	v_pk_add_f32 v[28:29], v[28:29], v[228:229]
	v_pk_add_f32 v[30:31], v[30:31], v[230:231]
	s_waitcnt vmcnt(7)
	v_pk_add_f32 v[32:33], v[32:33], v[232:233]
	v_pk_add_f32 v[34:35], v[34:35], v[234:235]
	s_waitcnt vmcnt(6)
	v_pk_add_f32 v[36:37], v[36:37], v[236:237]
	v_pk_add_f32 v[38:39], v[38:39], v[238:239]
	s_waitcnt vmcnt(5)
	v_pk_add_f32 v[40:41], v[40:41], v[240:241]
	v_pk_add_f32 v[42:43], v[42:43], v[242:243]
	s_waitcnt vmcnt(4)
	v_pk_add_f32 v[44:45], v[44:45], v[244:245]
	v_pk_add_f32 v[46:47], v[46:47], v[246:247]
	s_waitcnt vmcnt(3)
	v_pk_add_f32 v[48:49], v[48:49], v[160:161]
	v_pk_add_f32 v[50:51], v[50:51], v[162:163]
	s_waitcnt vmcnt(2)
	v_pk_add_f32 v[52:53], v[52:53], v[164:165]
	v_pk_add_f32 v[54:55], v[54:55], v[166:167]
	s_waitcnt vmcnt(1)
	v_pk_add_f32 v[56:57], v[56:57], v[168:169]
	v_pk_add_f32 v[58:59], v[58:59], v[170:171]
	s_waitcnt vmcnt(0)
	v_pk_add_f32 v[60:61], v[60:61], v[172:173]
	v_pk_add_f32 v[62:63], v[62:63], v[174:175]
	global_load_dwordx4 v[200:203], v140, s[78:79] sc0 sc1
	s_add_u32 s78, s78, 0x2000
	s_addc_u32 s79, s79, 0
	global_load_dwordx4 v[204:207], v140, s[78:79] sc0 sc1
	s_add_u32 s78, s78, 0x2000
	s_addc_u32 s79, s79, 0
	global_load_dwordx4 v[208:211], v140, s[78:79] sc0 sc1
	s_add_u32 s78, s78, 0x2000
	s_addc_u32 s79, s79, 0
	global_load_dwordx4 v[212:215], v140, s[78:79] sc0 sc1
	s_add_u32 s78, s78, 0x2000
	s_addc_u32 s79, s79, 0
	global_load_dwordx4 v[216:219], v140, s[78:79] sc0 sc1
	s_add_u32 s78, s78, 0x2000
	s_addc_u32 s79, s79, 0
	global_load_dwordx4 v[220:223], v140, s[78:79] sc0 sc1
	s_add_u32 s78, s78, 0x2000
	s_addc_u32 s79, s79, 0
	global_load_dwordx4 v[224:227], v140, s[78:79] sc0 sc1
	s_add_u32 s78, s78, 0x2000
	s_addc_u32 s79, s79, 0
	global_load_dwordx4 v[228:231], v140, s[78:79] sc0 sc1
	s_add_u32 s78, s78, 0x2000
	s_addc_u32 s79, s79, 0
	global_load_dwordx4 v[232:235], v140, s[78:79] sc0 sc1
	s_add_u32 s78, s78, 0x2000
	s_addc_u32 s79, s79, 0
	global_load_dwordx4 v[236:239], v140, s[78:79] sc0 sc1
	s_add_u32 s78, s78, 0x2000
	s_addc_u32 s79, s79, 0
	global_load_dwordx4 v[240:243], v140, s[78:79] sc0 sc1
	s_add_u32 s78, s78, 0x2000
	s_addc_u32 s79, s79, 0
	global_load_dwordx4 v[244:247], v140, s[78:79] sc0 sc1
	s_add_u32 s78, s78, 0x2000
	s_addc_u32 s79, s79, 0
	global_load_dwordx4 v[160:163], v140, s[78:79] sc0 sc1
	s_add_u32 s78, s78, 0x2000
	s_addc_u32 s79, s79, 0
	global_load_dwordx4 v[164:167], v140, s[78:79] sc0 sc1
	s_add_u32 s78, s78, 0x2000
	s_addc_u32 s79, s79, 0
	global_load_dwordx4 v[168:171], v140, s[78:79] sc0 sc1
	s_add_u32 s78, s78, 0x2000
	s_addc_u32 s79, s79, 0
	global_load_dwordx4 v[172:175], v140, s[78:79] sc0 sc1
	s_add_u32 s78, s78, 0x2000
	s_addc_u32 s79, s79, 0
	s_waitcnt vmcnt(15)
	v_pk_add_f32 v[64:65], v[64:65], v[200:201]
	v_pk_add_f32 v[66:67], v[66:67], v[202:203]
	s_waitcnt vmcnt(14)
	v_pk_add_f32 v[68:69], v[68:69], v[204:205]
	v_pk_add_f32 v[70:71], v[70:71], v[206:207]
	s_waitcnt vmcnt(13)
	v_pk_add_f32 v[72:73], v[72:73], v[208:209]
	v_pk_add_f32 v[74:75], v[74:75], v[210:211]
	s_waitcnt vmcnt(12)
	v_pk_add_f32 v[76:77], v[76:77], v[212:213]
	v_pk_add_f32 v[78:79], v[78:79], v[214:215]
	s_waitcnt vmcnt(11)
	v_pk_add_f32 v[80:81], v[80:81], v[216:217]
	v_pk_add_f32 v[82:83], v[82:83], v[218:219]
	s_waitcnt vmcnt(10)
	v_pk_add_f32 v[84:85], v[84:85], v[220:221]
	v_pk_add_f32 v[86:87], v[86:87], v[222:223]
	s_waitcnt vmcnt(9)
	v_pk_add_f32 v[88:89], v[88:89], v[224:225]
	v_pk_add_f32 v[90:91], v[90:91], v[226:227]
	s_waitcnt vmcnt(8)
	v_pk_add_f32 v[92:93], v[92:93], v[228:229]
	v_pk_add_f32 v[94:95], v[94:95], v[230:231]
	s_waitcnt vmcnt(7)
	v_pk_add_f32 v[96:97], v[96:97], v[232:233]
	v_pk_add_f32 v[98:99], v[98:99], v[234:235]
	s_waitcnt vmcnt(6)
	v_pk_add_f32 v[100:101], v[100:101], v[236:237]
	v_pk_add_f32 v[102:103], v[102:103], v[238:239]
	s_waitcnt vmcnt(5)
	v_pk_add_f32 v[104:105], v[104:105], v[240:241]
	v_pk_add_f32 v[106:107], v[106:107], v[242:243]
	s_waitcnt vmcnt(4)
	v_pk_add_f32 v[108:109], v[108:109], v[244:245]
	v_pk_add_f32 v[110:111], v[110:111], v[246:247]
	s_waitcnt vmcnt(3)
	v_pk_add_f32 v[112:113], v[112:113], v[160:161]
	v_pk_add_f32 v[114:115], v[114:115], v[162:163]
	s_waitcnt vmcnt(2)
	v_pk_add_f32 v[116:117], v[116:117], v[164:165]
	v_pk_add_f32 v[118:119], v[118:119], v[166:167]
	s_waitcnt vmcnt(1)
	v_pk_add_f32 v[120:121], v[120:121], v[168:169]
	v_pk_add_f32 v[122:123], v[122:123], v[170:171]
	s_waitcnt vmcnt(0)
	v_pk_add_f32 v[124:125], v[124:125], v[172:173]
	v_pk_add_f32 v[126:127], v[126:127], v[174:175]

; #define PG8_BAR __builtin_amdgcn_s_barrier()
; template <int KK, class Epi, class Sched, bool ALIGN_EPI = true>
; __device__ __forceinline__ void gemm_phase(LAS unsigned char* lds, const bf16* gA, const bf16* gBt, const Sched& S, const Epi& E, const int wid) {
;     ...
;         if constexpr (ALIGN_EPI) { if (wr == 0) PG8_BAR; }
;         E(acc, cur, wr, wc, fr, fq);
;         if (!has_next) break;
.LBB0_1297:
	s_cmp_lg_u32 s64, 0x100
	s_cbranch_scc1 .Lp5b_epi
	s_cmp_lg_u32 s42, 3
	s_cbranch_scc1 .Lp5b_epi
	s_bfe_u32 s65, s86, 0x20003
	s_and_b32 s66, s86, 7
	s_lshl_b32 s66, s66, 1
	s_bfe_u32 s67, s86, 0x10005
	s_add_i32 s66, s66, s67
	v_readlane_b32 s67, v249, 0
	v_lshlrev_b32_e32 v140, 4, v196
	s_nop 1
	s_lshl_b32 s68, s67, 10
	v_add_u32_e32 v140, s68, v140
	s_mul_i32 s68, s66, 3
	s_lshl_b32 s68, s68, 18
	s_add_u32 s70, s22, s68
	s_addc_u32 s71, s23, 0
	s_add_u32 s70, s70, 0xc00000
	s_addc_u32 s71, s71, 0
	s_cmp_eq_u32 s65, 0
	s_cbranch_scc1 .Lp5b_cons
	s_add_i32 s68, s65, -1
	s_lshl_b32 s68, s68, 18
	s_add_u32 s70, s70, s68
	s_addc_u32 s71, s71, 0
	s_nop 7
	global_store_dwordx4 v140, v[0:3], s[70:71] sc0 sc1
	s_add_u32 s70, s70, 0x2000
	s_addc_u32 s71, s71, 0
	global_store_dwordx4 v140, v[4:7], s[70:71] sc0 sc1
	s_add_u32 s70, s70, 0x2000
	s_addc_u32 s71, s71, 0
	global_store_dwordx4 v140, v[8:11], s[70:71] sc0 sc1
	s_add_u32 s70, s70, 0x2000
	s_addc_u32 s71, s71, 0
	global_store_dwordx4 v140, v[12:15], s[70:71] sc0 sc1
	s_add_u32 s70, s70, 0x2000
	s_addc_u32 s71, s71, 0
	global_store_dwordx4 v140, v[16:19], s[70:71] sc0 sc1
	s_add_u32 s70, s70, 0x2000
	s_addc_u32 s71, s71, 0
	global_store_dwordx4 v140, v[20:23], s[70:71] sc0 sc1
	s_add_u32 s70, s70, 0x2000
	s_addc_u32 s71, s71, 0
	global_store_dwordx4 v140, v[24:27], s[70:71] sc0 sc1
	s_add_u32 s70, s70, 0x2000
	s_addc_u32 s71, s71, 0
	global_store_dwordx4 v140, v[28:31], s[70:71] sc0 sc1
	s_add_u32 s70, s70, 0x2000
	s_addc_u32 s71, s71, 0
	global_store_dwordx4 v140, v[32:35], s[70:71] sc0 sc1
	s_add_u32 s70, s70, 0x2000
	s_addc_u32 s71, s71, 0
	global_store_dwordx4 v140, v[36:39], s[70:71] sc0 sc1
	s_add_u32 s70, s70, 0x2000
	s_addc_u32 s71, s71, 0
	global_store_dwordx4 v140, v[40:43], s[70:71] sc0 sc1
	s_add_u32 s70, s70, 0x2000
	s_addc_u32 s71, s71, 0
	global_store_dwordx4 v140, v[44:47], s[70:71] sc0 sc1
	s_add_u32 s70, s70, 0x2000
	s_addc_u32 s71, s71, 0
	global_store_dwordx4 v140, v[48:51], s[70:71] sc0 sc1
	s_add_u32 s70, s70, 0x2000
	s_addc_u32 s71, s71, 0
	global_store_dwordx4 v140, v[52:55], s[70:71] sc0 sc1
	s_add_u32 s70, s70, 0x2000
	s_addc_u32 s71, s71, 0
	global_store_dwordx4 v140, v[56:59], s[70:71] sc0 sc1
	s_add_u32 s70, s70, 0x2000
	s_addc_u32 s71, s71, 0
	global_store_dwordx4 v140, v[60:63], s[70:71] sc0 sc1
	s_add_u32 s70, s70, 0x2000
	s_addc_u32 s71, s71, 0
	global_store_dwordx4 v140, v[64:67], s[70:71] sc0 sc1
	s_add_u32 s70, s70, 0x2000
	s_addc_u32 s71, s71, 0
	global_store_dwordx4 v140, v[68:71], s[70:71] sc0 sc1
	s_add_u32 s70, s70, 0x2000
	s_addc_u32 s71, s71, 0
	global_store_dwordx4 v140, v[72:75], s[70:71] sc0 sc1
	s_add_u32 s70, s70, 0x2000
	s_addc_u32 s71, s71, 0
	global_store_dwordx4 v140, v[76:79], s[70:71] sc0 sc1
	s_add_u32 s70, s70, 0x2000
	s_addc_u32 s71, s71, 0
	global_store_dwordx4 v140, v[80:83], s[70:71] sc0 sc1
	s_add_u32 s70, s70, 0x2000
	s_addc_u32 s71, s71, 0
	global_store_dwordx4 v140, v[84:87], s[70:71] sc0 sc1
	s_add_u32 s70, s70, 0x2000
	s_addc_u32 s71, s71, 0
	global_store_dwordx4 v140, v[88:91], s[70:71] sc0 sc1
	s_add_u32 s70, s70, 0x2000
	s_addc_u32 s71, s71, 0
	global_store_dwordx4 v140, v[92:95], s[70:71] sc0 sc1
	s_add_u32 s70, s70, 0x2000
	s_addc_u32 s71, s71, 0
	global_store_dwordx4 v140, v[96:99], s[70:71] sc0 sc1
	s_add_u32 s70, s70, 0x2000
	s_addc_u32 s71, s71, 0
	global_store_dwordx4 v140, v[100:103], s[70:71] sc0 sc1
	s_add_u32 s70, s70, 0x2000
	s_addc_u32 s71, s71, 0
	global_store_dwordx4 v140, v[104:107], s[70:71] sc0 sc1
	s_add_u32 s70, s70, 0x2000
	s_addc_u32 s71, s71, 0
	global_store_dwordx4 v140, v[108:111], s[70:71] sc0 sc1
	s_add_u32 s70, s70, 0x2000
	s_addc_u32 s71, s71, 0
	global_store_dwordx4 v140, v[112:115], s[70:71] sc0 sc1
	s_add_u32 s70, s70, 0x2000
	s_addc_u32 s71, s71, 0
	global_store_dwordx4 v140, v[116:119], s[70:71] sc0 sc1
	s_add_u32 s70, s70, 0x2000
	s_addc_u32 s71, s71, 0
	global_store_dwordx4 v140, v[120:123], s[70:71] sc0 sc1
	s_add_u32 s70, s70, 0x2000
	s_addc_u32 s71, s71, 0
	global_store_dwordx4 v140, v[124:127], s[70:71] sc0 sc1
	s_waitcnt vmcnt(0)
	s_lshl_b32 s68, s66, 2
	s_add_i32 s68, s68, s65
	s_lshl_b32 s68, s68, 2
	v_mov_b32_e32 v141, s68
	v_mov_b32_e32 v142, 1
	s_mov_b64 s[72:73], exec
	s_mov_b64 exec, 1
	global_atomic_add v141, v142, s[20:21] offset:3200
	s_mov_b64 exec, s[72:73]
	s_branch .LBB0_1300

; #define PG8_BAR __builtin_amdgcn_s_barrier()
; template <int KK, class Epi, class Sched, bool ALIGN_EPI = true>
; __device__ __forceinline__ void gemm_phase(LAS unsigned char* lds, const bf16* gA, const bf16* gBt, const Sched& S, const Epi& E, const int wid) {
;     ...
;         if constexpr (ALIGN_EPI) { if (wr == 0) PG8_BAR; }
;         E(acc, cur, wr, wc, fr, fq);
.Lp5b_poll2:
	global_load_dword v142, v141, s[20:21] offset:3208 sc1
	s_waitcnt vmcnt(0)
	v_readfirstlane_b32 s69, v142
	s_nop 0
	s_cmp_ge_u32 s69, 16
	s_cbranch_scc1 .Lp5b_go2
	s_sleep 1
	s_branch .Lp5b_poll2

; #define PG8_BAR __builtin_amdgcn_s_barrier()
; template <int KK, class Epi, class Sched, bool ALIGN_EPI = true>
; __device__ __forceinline__ void gemm_phase(LAS unsigned char* lds, const bf16* gA, const bf16* gBt, const Sched& S, const Epi& E, const int wid) {
;     ...
;         if constexpr (ALIGN_EPI) { if (wr == 0) PG8_BAR; }
;         E(acc, cur, wr, wc, fr, fq);
.Lp5b_poll3:
	global_load_dword v142, v141, s[20:21] offset:3212 sc1
	s_waitcnt vmcnt(0)
	v_readfirstlane_b32 s69, v142
	s_nop 0
	s_cmp_ge_u32 s69, 16
	s_cbranch_scc1 .Lp5b_go3
	s_sleep 1
	s_branch .Lp5b_poll3

; #define PG8_BAR __builtin_amdgcn_s_barrier()
; template <int KK, class Epi, class Sched, bool ALIGN_EPI = true>
; __device__ __forceinline__ void gemm_phase(LAS unsigned char* lds, const bf16* gA, const bf16* gBt, const Sched& S, const Epi& E, const int wid) {
;     ...
;         if constexpr (ALIGN_EPI) { if (wr == 0) PG8_BAR; }
;         E(acc, cur, wr, wc, fr, fq);
.Lp5b_poll1:
	global_load_dword v142, v141, s[20:21] offset:3204 sc1
	s_waitcnt vmcnt(0)
	v_readfirstlane_b32 s69, v142
	s_nop 0
	s_cmp_ge_u32 s69, 16
	s_cbranch_scc1 .Lp5b_go1
	s_sleep 1
	s_branch .Lp5b_poll1
